# P0->P1 cg grid.sync replaced by a copy of the XCD-hierarchical barrier (one L2 writeback per XCD)
# speedup vs baseline: 1.0873x; 1.0016x over previous
.Lp0_cache_last1:
	s_waitcnt vmcnt(0)
	s_and_b32 s92, s25, 0xfff
	s_add_u32 s92, s92, 0x2000
	s_lshl_b32 s92, s92, 11
	s_add_u32 s26, s38, s92
	s_addc_u32 s27, s39, 0
	s_cmp_lt_u32 s25, 0x1000
	s_mov_b32 s93, 0x8600000
	s_cselect_b32 s93, 0x6e00000, s93
	s_add_u32 s26, s26, s93
	s_addc_u32 s27, s27, 0
	v_cvt_pk_bf16_f32 v32, v32, v33
	v_cvt_pk_bf16_f32 v33, v34, v35
	global_store_dwordx2 v3, v[32:33], s[26:27]
	v_cvt_pk_bf16_f32 v36, v36, v37
	v_cvt_pk_bf16_f32 v37, v38, v39
	global_store_dwordx2 v3, v[36:37], s[26:27] offset:512
	v_cvt_pk_bf16_f32 v40, v40, v41
	v_cvt_pk_bf16_f32 v41, v42, v43
	global_store_dwordx2 v3, v[40:41], s[26:27] offset:1024
	v_cvt_pk_bf16_f32 v44, v44, v45
	v_cvt_pk_bf16_f32 v45, v46, v47
	global_store_dwordx2 v3, v[44:45], s[26:27] offset:1536
.Lp0_cache_done:
	s_waitcnt vmcnt(0) lgkmcnt(0)
	s_barrier
	s_waitcnt vmcnt(0)
	s_barrier
	s_and_saveexec_b64 s[6:7], s[4:5]
	s_xor_b64 s[6:7], exec, s[6:7]
	s_cbranch_execz .Lgs_248
	s_add_i32 s8, 0, 0x27ff0
	v_mov_b32_e32 v0, s8
	s_waitcnt vmcnt(0) expcnt(0) lgkmcnt(0)
	ds_read_b32 v2, v0
	s_add_i32 s8, 0, 0x27ff4
	v_mov_b32_e32 v0, s8
	ds_read_b32 v0, v0
	s_waitcnt lgkmcnt(1)
	v_cmp_ne_u32_e32 vcc, 0, v2
	s_cbranch_vccnz .Lgs_211
	s_add_u32 s8, s38, 0x4200
	s_addc_u32 s9, s39, 0
	s_add_u32 s10, s38, 0x4400
	s_addc_u32 s11, s39, 0
	s_add_u32 s12, s38, 0x4500
	s_addc_u32 s13, s39, 0
	s_add_u32 s16, s38, 0x4600
	s_addc_u32 s17, s39, 0
	s_add_u32 s18, s38, 0x4700
	s_addc_u32 s19, s39, 0
	s_add_u32 s20, s38, 0x4800
	s_addc_u32 s21, s39, 0
	s_add_u32 s24, s38, 0x4900
	s_addc_u32 s25, s39, 0
	s_add_u32 s26, s38, 0x4a00
	s_addc_u32 s27, s39, 0
	s_add_u32 s28, s38, 0x4b00
	s_addc_u32 s29, s39, 0
	s_add_u32 s30, s38, 0x4c00
	s_addc_u32 s31, s39, 0
	s_add_u32 s40, s38, 0x4d00
	s_addc_u32 s41, s39, 0
	s_add_u32 s42, s38, 0x4e00
	s_addc_u32 s43, s39, 0
	s_add_u32 s50, s38, 0x4f00
	s_addc_u32 s51, s39, 0
	s_add_u32 s52, s38, 0x5000
	s_addc_u32 s53, s39, 0
	s_add_u32 s54, s38, 0x5100
	s_addc_u32 s55, s39, 0
	s_add_u32 s56, s38, 0x5200
	s_addc_u32 s57, s39, 0
	s_mul_i32 s35, s47, s85
	s_add_u32 s58, s38, 0x5300
	s_mul_i32 s35, s35, s46
	s_addc_u32 s59, s39, 0
	s_mov_b32 s66, 1
	v_mov_b32_e32 v16, 0
	s_branch .Lgs_199

.Lgs_247:
	s_or_b64 exec, exec, s[10:11]
.Lgs_248:
	s_or_b64 exec, exec, s[6:7]
	s_add_u32 s48, s38, 0x9e00000
	s_addc_u32 s49, s39, 0
	s_add_u32 s22, s38, 0x11f00000
	s_addc_u32 s23, s39, 0
	s_cmpk_lt_i32 s2, 0x1616
	v_mov_b32_e32 v0, v206
	s_cselect_b64 s[14:15], -1, 0
	v_mov_b32_e32 v9, v206
	s_barrier
	v_lshrrev_b32_e32 v11, 6, v206
	v_and_b32_e32 v8, 63, v206
	s_load_dwordx2 s[96:97], s[0:1], 0x118
	v_readfirstlane_b32 s86, v11
	v_and_b32_e32 v9, 15, v8
	v_lshrrev_b32_e32 v10, 4, v8
	s_mov_b32 s32, s86
	s_mov_b32 s101, 0
	s_mov_b32 s87, s2
	v_lshlrev_b32_e32 v11, 4, v10
	s_mul_i32 s100, s101, 0x400
	v_mov_b32_e32 v12, 0x800
	v_mul_u32_u24_e32 v12, v9, v12
	v_mov_b32_e32 v14, 0x800
	v_mul_u32_u24_e32 v14, v9, v14
	v_add_u32_e32 v12, v12, v11
	v_add_u32_e32 v14, v14, v11
	v_add_u32_e32 v12, s100, v12
	v_add_u32_e32 v14, s100, v14
	v_mov_b32_e32 v13, 0
	v_mov_b32_e32 v15, 0
	s_lshl_b32 s100, s32, 10
	s_add_u32 s100, s100, 0x20000
	v_lshlrev_b32_e32 v34, 4, v8
	v_add_u32_e32 v34, s100, v34
	s_lshl_b32 s100, s32, 8
	s_add_u32 s100, s100, 0x22000
	v_lshlrev_b32_e32 v35, 2, v8
	v_add_u32_e32 v35, s100, v35
	v_xor_b32_e32 v32, 16, v8
	v_lshlrev_b32_e32 v32, 2, v32
	v_xor_b32_e32 v33, 32, v8
	v_lshlrev_b32_e32 v33, 2, v33
	s_waitcnt lgkmcnt(0)
